# PROJ_EVEN all-P column tiles: permlane swaps + 16 dwordx4 stores per wave (as PROJ_ODD)
# speedup vs baseline: 1.0271x; 1.0064x over previous
; DI unsigned pack2(float a, float b) { f32x2 v = {a, b}; return __builtin_bit_cast(unsigned, __builtin_convertvector(v, hwbf16x2)); }
; template <int EPI>
; DI void gemm8_epilogue(const GemmArgs& g, f32x4 (&acc)[2][2][4][2], const int brow, const int bcol, const int wr, const int wc, const int fr, const int fq) {
;     ...
;         } else {
;           bf16_t* P = (bf16_t*)g.out0;
; #pragma unroll
;           for (int n = 0; n < 2; ++n) {
;             const int col = cb + n * 16 + fq * 4;
;             if (col < 2840) {
; #pragma unroll
;               for (int m = 0; m < 4; ++m) {
;                 u32x2 o; o.x = pack2(acc[ai][bj][m][n][0], acc[ai][bj][m][n][1]); o.y = pack2(acc[ai][bj][m][n][2], acc[ai][bj][m][n][3]);
;                 *(u32x2*)&P[(size_t)(r0 + m * 16) * LDP_E + col] = o;
;               }
;             }
;           }
.LBB0_576:
	s_lshl_b32 s23, s23, 8
	s_add_i32 s23, s23, s17
	v_or_b32_e32 v145, s23, v140
	v_lshl_or_b32 v138, s22, 8, v144
	s_cmp_lt_i32 s22, 9
	s_cbranch_scc0 .Lpe_orig
	v_and_b32_e32 v150, 12, v144
	v_add_u32_e32 v150, v138, v150
	v_mov_b32_e32 v151, 0
	v_lshl_add_u64 v[150:151], v[150:151], 1, s[60:61]
	s_mov_b64 s[40:41], 0x17000
	s_mov_b64 s[50:51], 0x73000
	v_mad_i64_i32 v[152:153], vcc, v145, s95, v[150:151]
	v_cvt_pk_bf16_f32 v126, v126, v127
	v_cvt_pk_bf16_f32 v127, v128, v129
	v_cvt_pk_bf16_f32 v128, v114, v115
	v_cvt_pk_bf16_f32 v129, v116, v117
	v_cvt_pk_bf16_f32 v94, v94, v95
	v_cvt_pk_bf16_f32 v95, v96, v97
	v_cvt_pk_bf16_f32 v96, v90, v91
	v_cvt_pk_bf16_f32 v97, v92, v93
	s_nop 1
	v_permlane32_swap_b32_e32 v126, v128
	v_permlane32_swap_b32_e32 v127, v129
	v_permlane32_swap_b32_e32 v94, v96
	v_permlane32_swap_b32_e32 v95, v97
	s_nop 1
	v_permlane16_swap_b32_e32 v126, v128
	v_permlane16_swap_b32_e32 v127, v129
	v_permlane16_swap_b32_e32 v94, v96
	v_permlane16_swap_b32_e32 v95, v97
	global_store_dwordx4 v[152:153], v[126:129], off
	global_store_dwordx4 v[152:153], v[94:97], off offset:256
	v_lshl_add_u64 v[152:153], v[152:153], 0, s[40:41]
	v_cvt_pk_bf16_f32 v122, v122, v123
	v_cvt_pk_bf16_f32 v123, v124, v125
	v_cvt_pk_bf16_f32 v124, v106, v107
	v_cvt_pk_bf16_f32 v125, v108, v109
	v_cvt_pk_bf16_f32 v86, v86, v87
	v_cvt_pk_bf16_f32 v87, v88, v89
	v_cvt_pk_bf16_f32 v88, v82, v83
	v_cvt_pk_bf16_f32 v89, v84, v85
	s_nop 1
	v_permlane32_swap_b32_e32 v122, v124
	v_permlane32_swap_b32_e32 v123, v125
	v_permlane32_swap_b32_e32 v86, v88
	v_permlane32_swap_b32_e32 v87, v89
	s_nop 1
	v_permlane16_swap_b32_e32 v122, v124
	v_permlane16_swap_b32_e32 v123, v125
	v_permlane16_swap_b32_e32 v86, v88
	v_permlane16_swap_b32_e32 v87, v89
	global_store_dwordx4 v[152:153], v[122:125], off
	global_store_dwordx4 v[152:153], v[86:89], off offset:256
	v_lshl_add_u64 v[152:153], v[152:153], 0, s[40:41]
	v_cvt_pk_bf16_f32 v118, v118, v119
	v_cvt_pk_bf16_f32 v119, v120, v121
	v_cvt_pk_bf16_f32 v120, v102, v103
	v_cvt_pk_bf16_f32 v121, v104, v105
	v_cvt_pk_bf16_f32 v78, v78, v79
	v_cvt_pk_bf16_f32 v79, v80, v81
	v_cvt_pk_bf16_f32 v80, v74, v75
	v_cvt_pk_bf16_f32 v81, v76, v77
	s_nop 1
	v_permlane32_swap_b32_e32 v118, v120
	v_permlane32_swap_b32_e32 v119, v121
	v_permlane32_swap_b32_e32 v78, v80
	v_permlane32_swap_b32_e32 v79, v81
	s_nop 1
	v_permlane16_swap_b32_e32 v118, v120
	v_permlane16_swap_b32_e32 v119, v121
	v_permlane16_swap_b32_e32 v78, v80
	v_permlane16_swap_b32_e32 v79, v81
	global_store_dwordx4 v[152:153], v[118:121], off
	global_store_dwordx4 v[152:153], v[78:81], off offset:256
	v_lshl_add_u64 v[152:153], v[152:153], 0, s[40:41]
	v_cvt_pk_bf16_f32 v110, v110, v111
	v_cvt_pk_bf16_f32 v111, v112, v113
	v_cvt_pk_bf16_f32 v112, v98, v99
	v_cvt_pk_bf16_f32 v113, v100, v101
	v_cvt_pk_bf16_f32 v70, v70, v71
	v_cvt_pk_bf16_f32 v71, v72, v73
	v_cvt_pk_bf16_f32 v72, v66, v67
	v_cvt_pk_bf16_f32 v73, v68, v69
	s_nop 1
	v_permlane32_swap_b32_e32 v110, v112
	v_permlane32_swap_b32_e32 v111, v113
	v_permlane32_swap_b32_e32 v70, v72
	v_permlane32_swap_b32_e32 v71, v73
	s_nop 1
	v_permlane16_swap_b32_e32 v110, v112
	v_permlane16_swap_b32_e32 v111, v113
	v_permlane16_swap_b32_e32 v70, v72
	v_permlane16_swap_b32_e32 v71, v73
	global_store_dwordx4 v[152:153], v[110:113], off
	global_store_dwordx4 v[152:153], v[70:73], off offset:256
	v_lshl_add_u64 v[152:153], v[152:153], 0, s[50:51]
	v_cvt_pk_bf16_f32 v62, v62, v63
	v_cvt_pk_bf16_f32 v63, v64, v65
	v_cvt_pk_bf16_f32 v64, v50, v51
	v_cvt_pk_bf16_f32 v65, v52, v53
	v_cvt_pk_bf16_f32 v30, v30, v31
	v_cvt_pk_bf16_f32 v31, v32, v33
	v_cvt_pk_bf16_f32 v32, v26, v27
	v_cvt_pk_bf16_f32 v33, v28, v29
	s_nop 1
	v_permlane32_swap_b32_e32 v62, v64
	v_permlane32_swap_b32_e32 v63, v65
	v_permlane32_swap_b32_e32 v30, v32
	v_permlane32_swap_b32_e32 v31, v33
	s_nop 1
	v_permlane16_swap_b32_e32 v62, v64
	v_permlane16_swap_b32_e32 v63, v65
	v_permlane16_swap_b32_e32 v30, v32
	v_permlane16_swap_b32_e32 v31, v33
	global_store_dwordx4 v[152:153], v[62:65], off
	global_store_dwordx4 v[152:153], v[30:33], off offset:256
	v_lshl_add_u64 v[152:153], v[152:153], 0, s[40:41]
	v_cvt_pk_bf16_f32 v58, v58, v59
	v_cvt_pk_bf16_f32 v59, v60, v61
	v_cvt_pk_bf16_f32 v60, v42, v43
	v_cvt_pk_bf16_f32 v61, v44, v45
	v_cvt_pk_bf16_f32 v22, v22, v23
	v_cvt_pk_bf16_f32 v23, v24, v25
	v_cvt_pk_bf16_f32 v24, v18, v19
	v_cvt_pk_bf16_f32 v25, v20, v21
	s_nop 1
	v_permlane32_swap_b32_e32 v58, v60
	v_permlane32_swap_b32_e32 v59, v61
	v_permlane32_swap_b32_e32 v22, v24
	v_permlane32_swap_b32_e32 v23, v25
	s_nop 1
	v_permlane16_swap_b32_e32 v58, v60
	v_permlane16_swap_b32_e32 v59, v61
	v_permlane16_swap_b32_e32 v22, v24
	v_permlane16_swap_b32_e32 v23, v25
	global_store_dwordx4 v[152:153], v[58:61], off
	global_store_dwordx4 v[152:153], v[22:25], off offset:256
	v_lshl_add_u64 v[152:153], v[152:153], 0, s[40:41]
	v_cvt_pk_bf16_f32 v54, v54, v55
	v_cvt_pk_bf16_f32 v55, v56, v57
	v_cvt_pk_bf16_f32 v56, v38, v39
	v_cvt_pk_bf16_f32 v57, v40, v41
	v_cvt_pk_bf16_f32 v14, v14, v15
	v_cvt_pk_bf16_f32 v15, v16, v17
	v_cvt_pk_bf16_f32 v16, v10, v11
	v_cvt_pk_bf16_f32 v17, v12, v13
	s_nop 1
	v_permlane32_swap_b32_e32 v54, v56
	v_permlane32_swap_b32_e32 v55, v57
	v_permlane32_swap_b32_e32 v14, v16
	v_permlane32_swap_b32_e32 v15, v17
	s_nop 1
	v_permlane16_swap_b32_e32 v54, v56
	v_permlane16_swap_b32_e32 v55, v57
	v_permlane16_swap_b32_e32 v14, v16
	v_permlane16_swap_b32_e32 v15, v17
	global_store_dwordx4 v[152:153], v[54:57], off
	global_store_dwordx4 v[152:153], v[14:17], off offset:256
	v_lshl_add_u64 v[152:153], v[152:153], 0, s[40:41]
	v_cvt_pk_bf16_f32 v46, v46, v47
	v_cvt_pk_bf16_f32 v47, v48, v49
	v_cvt_pk_bf16_f32 v48, v34, v35
	v_cvt_pk_bf16_f32 v49, v36, v37
	v_cvt_pk_bf16_f32 v6, v6, v7
	v_cvt_pk_bf16_f32 v7, v8, v9
	v_cvt_pk_bf16_f32 v8, v2, v3
	v_cvt_pk_bf16_f32 v9, v4, v5
	s_nop 1
	v_permlane32_swap_b32_e32 v46, v48
	v_permlane32_swap_b32_e32 v47, v49
	v_permlane32_swap_b32_e32 v6, v8
	v_permlane32_swap_b32_e32 v7, v9
	s_nop 1
	v_permlane16_swap_b32_e32 v46, v48
	v_permlane16_swap_b32_e32 v47, v49
	v_permlane16_swap_b32_e32 v6, v8
	v_permlane16_swap_b32_e32 v7, v9
	global_store_dwordx4 v[152:153], v[46:49], off
	global_store_dwordx4 v[152:153], v[6:9], off offset:256
	s_branch .LBB0_596
; DI unsigned pack2(float a, float b) { f32x2 v = {a, b}; return __builtin_bit_cast(unsigned, __builtin_convertvector(v, hwbf16x2)); }
; template <int EPI>
; DI void gemm8_epilogue(const GemmArgs& g, f32x4 (&acc)[2][2][4][2], const int brow, const int bcol, const int wr, const int wc, const int fr, const int fq) {
;     ...
;         } else {
;           bf16_t* P = (bf16_t*)g.out0;
; #pragma unroll
;           for (int n = 0; n < 2; ++n) {
;             const int col = cb + n * 16 + fq * 4;
;             if (col < 2840) {
; #pragma unroll
;               for (int m = 0; m < 4; ++m) {
;                 u32x2 o; o.x = pack2(acc[ai][bj][m][n][0], acc[ai][bj][m][n][1]); o.y = pack2(acc[ai][bj][m][n][2], acc[ai][bj][m][n][3]);
;                 *(u32x2*)&P[(size_t)(r0 + m * 16) * LDP_E + col] = o;
;               }
;             }
;           }
.Lpe_orig:
	v_cmp_gt_i32_e64 s[38:39], s27, v138
	v_ashrrev_i32_e32 v139, 31, v138
	v_or_b32_e32 v147, 16, v145
	v_or_b32_e32 v146, 32, v145
	v_or_b32_e32 v0, 48, v145
	s_and_saveexec_b64 s[40:41], s[38:39]
	s_cbranch_execz .LBB0_578
	v_lshl_add_u64 v[148:149], v[138:139], 1, s[60:61]
	v_cvt_pk_bf16_f32 v126, v126, v127
	v_cvt_pk_bf16_f32 v127, v128, v129
	v_mad_i64_i32 v[128:129], s[24:25], v145, s95, v[148:149]
	v_cvt_pk_bf16_f32 v122, v122, v123
	v_cvt_pk_bf16_f32 v123, v124, v125
	v_mad_i64_i32 v[124:125], s[24:25], v147, s95, v[148:149]
	v_cvt_pk_bf16_f32 v118, v118, v119
	v_cvt_pk_bf16_f32 v119, v120, v121
	v_mad_i64_i32 v[120:121], s[24:25], v146, s95, v[148:149]
	v_cvt_pk_bf16_f32 v110, v110, v111
	v_cvt_pk_bf16_f32 v111, v112, v113
	v_mad_i64_i32 v[112:113], s[24:25], v0, s95, v[148:149]
	global_store_dwordx2 v[128:129], v[126:127], off
	global_store_dwordx2 v[124:125], v[122:123], off
	global_store_dwordx2 v[120:121], v[118:119], off
	global_store_dwordx2 v[112:113], v[110:111], off
